# LRU scan loops: the four LDS gate reads of a token group issued together at group start with counted lgkmcnt waits
# baseline (speedup 1.0000x reference)
; __device__ __forceinline__ float sigmoidf_(float x) { return __builtin_amdgcn_rcpf(1.f + __expf(-x)); }
; template <bool FINAL>
; __device__ __forceinline__ void lru_job(const Params& P, int j, int b, int chunk, int h, char* ldsw) {
;     ...
; #pragma unroll
;       for (int q = 0; q < 4; ++q) {
;         const int tt = tg + q;
;         const float xt = xq[q];
;         float xcv = cb + v0 * cw0 + v1 * cw1 + v2 * cw2 + xt * cw3;
;         v0 = v1; v1 = v2; v2 = xt;
;         float rr = sigmoidf_(rbuf[tt * 64 + lane] + ba);
;         float ii = sigmoidf_(ibuf[tt * 64 + lane] + bx);
;         float la = -8.f * rr * sp;
;         float a = __expf(la);
;         const float x2 = 2.f * la;
;         const float om = (x2 > -0.03f) ? -x2 * (1.f + x2 * (0.5f + x2 * (0.16666667f + x2 * 0.041666667f))) : 1.f - a * a;
;         float bc = __builtin_amdgcn_sqrtf(om);
;         hst = a * hst + bc * ii * xcv;
;         if (FINAL) {
;           Y[(rowb + tt) * 1024 + ch] = f2bf(hst * gelu_tanh(yq[q]));
;         } else {
;           Ap *= a;
;         }
;       }
.LBB0_477:
	ds_read2st64_b32 v[156:157], v8 offset1:32
	ds_read2st64_b32 v[158:159], v8 offset0:1 offset1:33
	ds_read2st64_b32 v[160:161], v8 offset0:2 offset1:34
	ds_read2st64_b32 v[162:163], v8 offset0:3 offset1:35
	s_waitcnt lgkmcnt(3)
	v_add_f32_e32 v4, v122, v156
	v_mul_f32_e32 v4, 0xbfb8aa3b, v4
	v_exp_f32_e32 v4, v4
	s_nop 0
	v_add_f32_e32 v4, 1.0, v4
	v_rcp_f32_e32 v4, v4
	s_nop 0
	v_mul_f32_e32 v4, 0xc1000000, v4
	v_mul_f32_e32 v4, v124, v4
	v_mul_f32_e32 v6, 0x3fb8aa3b, v4
	v_exp_f32_e32 v185, v6
	v_add_f32_e32 v6, v4, v4
	v_cmp_nlt_f32_e32 vcc, s51, v6
	s_and_saveexec_b64 s[36:37], vcc
	s_xor_b64 s[36:37], exec, s[36:37]
	v_fma_f32 v4, -v185, v185, 1.0
	s_andn2_saveexec_b64 s[36:37], s[36:37]
	v_fmamk_f32 v4, v6, 0x3d2aaaab, v222
	v_fma_f32 v4, v6, v4, 0.5
	v_fma_f32 v4, v6, v4, 1.0
	v_mul_f32_e64 v4, v4, -v6
	s_or_b64 exec, exec, s[36:37]
	v_add_f32_e32 v5, v123, v157
	v_mul_f32_e32 v5, 0xbfb8aa3b, v5
	v_exp_f32_e32 v5, v5
	v_sqrt_f32_e32 v4, v4
	v_fma_f32 v6, v76, v108, v84
	v_fmac_f32_e32 v6, v78, v113
	v_add_f32_e32 v5, 1.0, v5
	v_rcp_f32_e32 v5, v5
	v_fmac_f32_e32 v6, v80, v9
	v_fmac_f32_e32 v6, v82, v62
	v_mov_b32_e32 v108, v0
	v_mul_f32_e32 v4, v5, v4
	v_mul_f32_e32 v5, v6, v4
	v_mul_f32_e32 v4, 0x3d372713, v0
	v_mul_f32_e32 v4, v0, v4
	v_fma_f32 v4, v0, v4, v0
	v_mul_f32_e32 v4, 0x3f4c422a, v4
	v_add_f32_e32 v4, v4, v4
	v_mul_f32_e32 v4, 0x3fb8aa3b, v4
	v_exp_f32_e32 v4, v4
	v_pk_mul_f32 v[6:7], v[108:109], v[184:185]
	v_add_f32_e32 v4, 1.0, v4
	v_rcp_f32_e32 v4, v4
	s_nop 0
	v_fma_f32 v4, v4, -2.0, 1.0
	v_add_f32_e32 v4, 1.0, v4
	v_pk_mul_f32 v[6:7], v[6:7], v[4:5]
	v_pk_fma_f32 v[4:5], v[108:109], v[184:185], v[4:5]
	s_nop 0
	v_pk_mul_f32 v[6:7], v[6:7], v[4:5] op_sel:[0,1] op_sel_hi:[1,0]
	s_nop 0
	v_bfe_u32 v0, v6, 16, 1
	v_add3_u32 v0, v6, v0, s25
	v_lshl_add_u64 v[6:7], s[6:7], 0, v[106:107]
	global_store_short_d16_hi v[6:7], v0, off
	s_waitcnt lgkmcnt(2)
	v_add_f32_e32 v0, v122, v158
	v_mul_f32_e32 v0, 0xbfb8aa3b, v0
	v_exp_f32_e32 v0, v0
	s_nop 0
	v_add_f32_e32 v0, 1.0, v0
	v_rcp_f32_e32 v0, v0
	s_nop 0
	v_mul_f32_e32 v0, 0xc1000000, v0
	v_mul_f32_e32 v0, v124, v0
	v_mul_f32_e32 v4, 0x3fb8aa3b, v0
	v_exp_f32_e32 v185, v4
	v_add_f32_e32 v4, v0, v0
	v_cmp_nlt_f32_e32 vcc, s51, v4
	s_and_saveexec_b64 s[36:37], vcc
	s_xor_b64 s[36:37], exec, s[36:37]
	v_fma_f32 v0, -v185, v185, 1.0
	s_andn2_saveexec_b64 s[36:37], s[36:37]
	v_fmamk_f32 v0, v4, 0x3d2aaaab, v222
	v_fma_f32 v0, v4, v0, 0.5
	v_fma_f32 v0, v4, v0, 1.0
	v_mul_f32_e64 v0, v0, -v4
	s_or_b64 exec, exec, s[36:37]
	v_add_f32_e32 v6, v123, v159
	v_mul_f32_e32 v6, 0xbfb8aa3b, v6
	v_exp_f32_e32 v6, v6
	v_sqrt_f32_e32 v0, v0
	v_fma_f32 v4, v76, v113, v84
	v_fmac_f32_e32 v4, v78, v9
	v_add_f32_e32 v6, 1.0, v6
	v_rcp_f32_e32 v6, v6
	v_fmac_f32_e32 v4, v80, v62
	v_fmac_f32_e32 v4, v82, v63
	v_mul_f32_e32 v0, v6, v0
	v_mul_f32_e32 v7, v4, v0
	v_mul_f32_e32 v0, 0x3d372713, v1
	v_mul_f32_e32 v0, v1, v0
	v_fma_f32 v0, v1, v0, v1
	v_mul_f32_e32 v0, 0x3f4c422a, v0
	v_add_f32_e32 v0, v0, v0
	v_mul_f32_e32 v0, 0x3fb8aa3b, v0
	v_exp_f32_e32 v0, v0
	v_mov_b32_e32 v4, v1
	v_add_f32_e32 v0, 1.0, v0
	v_rcp_f32_e32 v0, v0
	s_nop 0
	v_fma_f32 v0, v0, -2.0, 1.0
	v_add_f32_e32 v6, 1.0, v0
	v_pk_mul_f32 v[0:1], v[4:5], v[184:185]
	s_nop 0
	v_pk_mul_f32 v[10:11], v[0:1], v[6:7]
	v_pk_fma_f32 v[0:1], v[4:5], v[184:185], v[6:7]
	s_nop 0
	v_pk_mul_f32 v[4:5], v[10:11], v[0:1] op_sel:[0,1] op_sel_hi:[1,0]
	s_nop 0
	v_bfe_u32 v0, v4, 16, 1
	v_add3_u32 v0, v4, v0, s25
	v_lshl_add_u64 v[4:5], s[70:71], 0, v[106:107]
	global_store_short_d16_hi v[4:5], v0, off
	s_waitcnt lgkmcnt(1)
; __device__ __forceinline__ float sigmoidf_(float x) { return __builtin_amdgcn_rcpf(1.f + __expf(-x)); }
; template <bool FINAL>
; __device__ __forceinline__ void lru_job(const Params& P, int j, int b, int chunk, int h, char* ldsw) {
;     ...
; #pragma unroll
;       for (int q = 0; q < 4; ++q) {
;         const int tt = tg + q;
;         const float xt = xq[q];
;         float xcv = cb + v0 * cw0 + v1 * cw1 + v2 * cw2 + xt * cw3;
;         v0 = v1; v1 = v2; v2 = xt;
;         float rr = sigmoidf_(rbuf[tt * 64 + lane] + ba);
;         float ii = sigmoidf_(ibuf[tt * 64 + lane] + bx);
;         float la = -8.f * rr * sp;
;         float a = __expf(la);
;         const float x2 = 2.f * la;
;         const float om = (x2 > -0.03f) ? -x2 * (1.f + x2 * (0.5f + x2 * (0.16666667f + x2 * 0.041666667f))) : 1.f - a * a;
;         float bc = __builtin_amdgcn_sqrtf(om);
;         hst = a * hst + bc * ii * xcv;
;         if (FINAL) {
;           Y[(rowb + tt) * 1024 + ch] = f2bf(hst * gelu_tanh(yq[q]));
;         } else {
;           Ap *= a;
;         }
;       }
; #pragma unroll
;       for (int q = 0; q < 4; ++q) { xq[q] = xqn[q]; yq[q] = yqn[q]; }
	v_add_f32_e32 v0, v122, v160
	v_mul_f32_e32 v0, 0xbfb8aa3b, v0
	v_exp_f32_e32 v0, v0
	s_nop 0
	v_add_f32_e32 v0, 1.0, v0
	v_rcp_f32_e32 v0, v0
	s_nop 0
	v_mul_f32_e32 v0, 0xc1000000, v0
	v_mul_f32_e32 v0, v124, v0
	v_mul_f32_e32 v4, 0x3fb8aa3b, v0
	v_exp_f32_e32 v185, v4
	v_add_f32_e32 v4, v0, v0
	v_cmp_nlt_f32_e32 vcc, s51, v4
	s_and_saveexec_b64 s[36:37], vcc
	s_xor_b64 s[36:37], exec, s[36:37]
	v_fma_f32 v0, -v185, v185, 1.0
	s_andn2_saveexec_b64 s[36:37], s[36:37]
	v_fmamk_f32 v0, v4, 0x3d2aaaab, v222
	v_fma_f32 v0, v4, v0, 0.5
	v_fma_f32 v0, v4, v0, 1.0
	v_mul_f32_e64 v0, v0, -v4
	s_or_b64 exec, exec, s[36:37]
	v_add_f32_e32 v5, v123, v161
	v_mul_f32_e32 v5, 0xbfb8aa3b, v5
	v_exp_f32_e32 v5, v5
	v_sqrt_f32_e32 v0, v0
	v_fma_f32 v4, v76, v9, v84
	v_fmac_f32_e32 v4, v78, v62
	v_add_f32_e32 v5, 1.0, v5
	v_rcp_f32_e32 v5, v5
	v_fmac_f32_e32 v4, v80, v63
	v_fmac_f32_e32 v4, v82, v64
	v_mul_f32_e32 v0, v5, v0
	v_mul_f32_e32 v5, v4, v0
	v_mul_f32_e32 v0, 0x3d372713, v2
	v_mul_f32_e32 v0, v2, v0
	v_fma_f32 v0, v2, v0, v2
	v_mul_f32_e32 v0, 0x3f4c422a, v0
	v_add_f32_e32 v0, v0, v0
	v_mul_f32_e32 v0, 0x3fb8aa3b, v0
	v_exp_f32_e32 v0, v0
	s_nop 0
	v_add_f32_e32 v0, 1.0, v0
	v_rcp_f32_e32 v0, v0
	s_nop 0
	v_fma_f32 v0, v0, -2.0, 1.0
	v_add_f32_e32 v4, 1.0, v0
	v_mov_b32_e32 v0, v2
	v_pk_mul_f32 v[6:7], v[0:1], v[184:185]
	s_nop 0
	v_pk_mul_f32 v[6:7], v[6:7], v[4:5]
	v_pk_fma_f32 v[4:5], v[0:1], v[184:185], v[4:5]
	s_nop 0
	v_pk_mul_f32 v[0:1], v[6:7], v[4:5] op_sel:[0,1] op_sel_hi:[1,0]
	v_bfe_u32 v1, v0, 16, 1
	v_add3_u32 v2, v0, v1, s25
	v_lshl_add_u64 v[0:1], s[68:69], 0, v[106:107]
	global_store_short_d16_hi v[0:1], v2, off
	s_waitcnt lgkmcnt(0)
	v_add_f32_e32 v2, v122, v162
	v_mul_f32_e32 v2, 0xbfb8aa3b, v2
	v_exp_f32_e32 v2, v2
	s_nop 0
	v_add_f32_e32 v2, 1.0, v2
	v_rcp_f32_e32 v2, v2
	s_nop 0
	v_mul_f32_e32 v2, 0xc1000000, v2
	v_mul_f32_e32 v2, v124, v2
	v_mul_f32_e32 v4, 0x3fb8aa3b, v2
	v_exp_f32_e32 v185, v4
	v_add_f32_e32 v4, v2, v2
	v_cmp_nlt_f32_e32 vcc, s51, v4
	s_and_saveexec_b64 s[36:37], vcc
	s_xor_b64 s[36:37], exec, s[36:37]
	v_fma_f32 v2, -v185, v185, 1.0
	s_andn2_saveexec_b64 s[36:37], s[36:37]
	v_fmamk_f32 v2, v4, 0x3d2aaaab, v222
	v_fma_f32 v2, v4, v2, 0.5
	v_fma_f32 v2, v4, v2, 1.0
	v_mul_f32_e64 v2, v2, -v4
	s_or_b64 exec, exec, s[36:37]
	v_add_f32_e32 v4, v123, v163
	v_mul_f32_e32 v7, 0x3d372713, v3
	v_mul_f32_e32 v7, v3, v7
	v_mov_b32_e32 v9, v3
	v_fmac_f32_e32 v9, v9, v7
	v_mul_f32_e32 v7, 0x3f4c422a, v9
	v_add_f32_e32 v7, v7, v7
	s_add_u32 s8, s8, 0x3000
	v_mul_f32_e32 v4, 0xbfb8aa3b, v4
	v_mul_f32_e32 v7, 0x3fb8aa3b, v7
	s_addc_u32 s9, s9, 0
	v_exp_f32_e32 v4, v4
	v_exp_f32_e32 v7, v7
	s_add_u32 s10, s10, 0x3000
	s_addc_u32 s11, s11, 0
	s_add_u32 s52, s52, 0x3000
	s_addc_u32 s53, s53, 0
	v_add_f32_e32 v4, 1.0, v4
	v_add_f32_e32 v7, 1.0, v7
	s_add_u32 s54, s54, 0x3000
	v_rcp_f32_e32 v4, v4
	v_sqrt_f32_e32 v2, v2
	v_rcp_f32_e32 v7, v7
	s_addc_u32 s55, s55, 0
	s_add_u32 s60, s60, 0x3000
	s_addc_u32 s61, s61, 0
	v_fma_f32 v6, v76, v62, v84
	s_add_u32 s62, s62, 0x3000
	v_fmac_f32_e32 v6, v78, v63
	v_mul_f32_e32 v2, v4, v2
	v_fma_f32 v4, v7, -2.0, 1.0
	s_addc_u32 s63, s63, 0
	v_fmac_f32_e32 v6, v80, v64
	v_add_f32_e32 v7, 1.0, v4
	v_mov_b32_e32 v4, v3
	s_add_u32 s68, s68, 0x2000
	v_fmac_f32_e32 v6, v82, v65
	v_pk_mul_f32 v[108:109], v[4:5], v[184:185]
	s_addc_u32 s69, s69, 0
	v_mul_f32_e32 v3, v108, v7
	v_fmac_f32_e32 v109, v6, v2
	s_add_u32 s70, s70, 0x2000
	v_mul_f32_e32 v2, v3, v109
	s_addc_u32 s71, s71, 0
	v_bfe_u32 v3, v2, 16, 1
	s_add_u32 s6, s6, 0x2000
	v_add3_u32 v2, v2, v3, s25
	v_mov_b32_e32 v108, v63
	v_mov_b32_e32 v113, v64
	v_add_u32_e32 v8, 0x400, v8
	s_addc_u32 s7, s7, 0
	s_and_b64 vcc, exec, s[72:73]
	global_store_short_d16_hi v[0:1], v2, off offset:2048
	s_cbranch_vccnz .LBB0_473
	v_mov_b32_e32 v9, v65
	s_waitcnt vmcnt(4)
	v_lshlrev_b32_e32 v66, 16, v153
	v_lshlrev_b32_e32 v70, 16, v154
	v_lshlrev_b32_e32 v67, 16, v12
	v_lshlrev_b32_e32 v71, 16, v14
	v_lshlrev_b32_e32 v68, 16, v13
	v_lshlrev_b32_e32 v72, 16, v150
	v_lshlrev_b32_e32 v69, 16, v151
	v_lshlrev_b32_e32 v73, 16, v152
	v_mov_b64_e32 v[62:63], v[66:67]
	v_mov_b64_e32 v[0:1], v[70:71]
	v_mov_b64_e32 v[64:65], v[68:69]
	v_mov_b64_e32 v[2:3], v[72:73]
	s_branch .LBB0_475

; __device__ __forceinline__ float sigmoidf_(float x) { return __builtin_amdgcn_rcpf(1.f + __expf(-x)); }
; template <bool FINAL>
; __device__ __forceinline__ void lru_job(const Params& P, int j, int b, int chunk, int h, char* ldsw) {
;     ...
; #pragma unroll
;       for (int q = 0; q < 4; ++q) {
;         const int tt = tg + q;
;         const float xt = xq[q];
;         float xcv = cb + v0 * cw0 + v1 * cw1 + v2 * cw2 + xt * cw3;
;         v0 = v1; v1 = v2; v2 = xt;
;         float rr = sigmoidf_(rbuf[tt * 64 + lane] + ba);
;         float ii = sigmoidf_(ibuf[tt * 64 + lane] + bx);
;         float la = -8.f * rr * sp;
;         float a = __expf(la);
;         const float x2 = 2.f * la;
;         const float om = (x2 > -0.03f) ? -x2 * (1.f + x2 * (0.5f + x2 * (0.16666667f + x2 * 0.041666667f))) : 1.f - a * a;
;         float bc = __builtin_amdgcn_sqrtf(om);
;         hst = a * hst + bc * ii * xcv;
;         if (FINAL) {
;           Y[(rowb + tt) * 1024 + ch] = f2bf(hst * gelu_tanh(yq[q]));
;         } else {
;           Ap *= a;
;         }
;       }
.LBB0_543:
	ds_read2st64_b32 v[202:203], v10 offset1:32
	ds_read2st64_b32 v[204:205], v10 offset0:1 offset1:33
	ds_read2st64_b32 v[206:207], v10 offset0:2 offset1:34
	ds_read2st64_b32 v[234:235], v10 offset0:3 offset1:35
	s_waitcnt lgkmcnt(3)
	v_add_f32_e32 v2, v174, v202
	v_mul_f32_e32 v2, 0xbfb8aa3b, v2
	v_exp_f32_e32 v2, v2
	s_nop 0
	v_add_f32_e32 v2, 1.0, v2
	v_rcp_f32_e32 v2, v2
	s_nop 0
	v_mul_f32_e32 v2, 0xc1000000, v2
	v_mul_f32_e32 v2, v176, v2
	v_mul_f32_e32 v4, 0x3fb8aa3b, v2
	v_exp_f32_e32 v12, v4
	v_add_f32_e32 v2, v2, v2
	v_cmp_nlt_f32_e32 vcc, s51, v2
	s_and_saveexec_b64 s[6:7], vcc
	s_xor_b64 s[6:7], exec, s[6:7]
	v_fma_f32 v14, -v12, v12, 1.0
	s_andn2_saveexec_b64 s[6:7], s[6:7]
	v_fmamk_f32 v4, v2, 0x3d2aaaab, v222
	v_fma_f32 v4, v2, v4, 0.5
	v_fma_f32 v4, v2, v4, 1.0
	v_mul_f32_e64 v14, v4, -v2
	s_or_b64 exec, exec, s[6:7]
	s_waitcnt lgkmcnt(2)
	v_add_f32_e32 v2, v174, v204
	v_mul_f32_e32 v2, 0xbfb8aa3b, v2
	v_exp_f32_e32 v2, v2
	s_nop 0
	v_add_f32_e32 v2, 1.0, v2
	v_rcp_f32_e32 v2, v2
	s_nop 0
	v_mul_f32_e32 v2, 0xc1000000, v2
	v_mul_f32_e32 v2, v176, v2
	v_mul_f32_e32 v4, 0x3fb8aa3b, v2
	v_exp_f32_e32 v13, v4
	v_add_f32_e32 v2, v2, v2
	v_cmp_nlt_f32_e32 vcc, s51, v2
	s_and_saveexec_b64 s[6:7], vcc
	s_xor_b64 s[6:7], exec, s[6:7]
	v_fma_f32 v15, -v13, v13, 1.0
	s_andn2_saveexec_b64 s[6:7], s[6:7]
	v_fmamk_f32 v4, v2, 0x3d2aaaab, v222
	v_fma_f32 v4, v2, v4, 0.5
	v_fma_f32 v4, v2, v4, 1.0
	v_mul_f32_e64 v15, v4, -v2
	s_or_b64 exec, exec, s[6:7]
	s_waitcnt lgkmcnt(1)
	v_add_f32_e32 v2, v174, v206
	v_mul_f32_e32 v2, 0xbfb8aa3b, v2
	v_exp_f32_e32 v2, v2
	s_nop 0
	v_add_f32_e32 v2, 1.0, v2
	v_rcp_f32_e32 v2, v2
	s_nop 0
	v_mul_f32_e32 v2, 0xc1000000, v2
	v_mul_f32_e32 v4, v176, v2
	v_mul_f32_e32 v2, 0x3fb8aa3b, v4
	v_exp_f32_e32 v2, v2
	v_add_f32_e32 v4, v4, v4
	v_cmp_nlt_f32_e32 vcc, s51, v4
	s_and_saveexec_b64 s[6:7], vcc
	s_xor_b64 s[6:7], exec, s[6:7]
	v_fma_f32 v6, -v2, v2, 1.0
	s_andn2_saveexec_b64 s[6:7], s[6:7]
	v_fmamk_f32 v6, v4, 0x3d2aaaab, v222
	v_fma_f32 v6, v4, v6, 0.5
	v_fma_f32 v6, v4, v6, 1.0
	v_mul_f32_e64 v6, v6, -v4
	s_or_b64 exec, exec, s[6:7]
	s_waitcnt lgkmcnt(0)
	v_add_f32_e32 v4, v174, v234
	v_mul_f32_e32 v4, 0xbfb8aa3b, v4
	v_exp_f32_e32 v4, v4
	s_nop 0
	v_add_f32_e32 v4, 1.0, v4
	v_rcp_f32_e32 v4, v4
	s_nop 0
	v_mul_f32_e32 v4, 0xc1000000, v4
	v_mul_f32_e32 v8, v176, v4
	v_mul_f32_e32 v4, 0x3fb8aa3b, v8
	v_exp_f32_e32 v4, v4
	v_add_f32_e32 v16, v8, v8
	v_cmp_nlt_f32_e32 vcc, s51, v16
	s_and_saveexec_b64 s[6:7], vcc
	s_xor_b64 s[6:7], exec, s[6:7]
	v_fma_f32 v8, -v4, v4, 1.0
	s_andn2_saveexec_b64 s[6:7], s[6:7]
	v_fmamk_f32 v8, v16, 0x3d2aaaab, v222
	v_fma_f32 v8, v16, v8, 0.5
	v_fma_f32 v8, v16, v8, 1.0
	v_mul_f32_e64 v8, v8, -v16
	s_or_b64 exec, exec, s[6:7]
	v_add_f32_e32 v3, v175, v203
	v_mul_f32_e32 v3, 0xbfb8aa3b, v3
	v_exp_f32_e32 v3, v3
	v_add_f32_e32 v5, v175, v205
	v_mul_f32_e32 v5, 0xbfb8aa3b, v5
	v_exp_f32_e32 v5, v5
	v_add_f32_e32 v3, 1.0, v3
	v_sqrt_f32_e32 v14, v14
	v_rcp_f32_e32 v3, v3
	v_add_f32_e32 v5, 1.0, v5
	v_fma_f32 v16, v142, v114, v150
	v_rcp_f32_e32 v5, v5
	v_sqrt_f32_e32 v15, v15
	v_fmac_f32_e32 v16, v144, v113
	v_mul_f32_e32 v3, v3, v14
	v_fma_f32 v14, v142, v113, v150
	v_fmac_f32_e32 v16, v146, v11
	v_fmac_f32_e32 v14, v144, v11
	v_fmac_f32_e32 v16, v149, v132
	v_fmac_f32_e32 v14, v146, v132
	v_mul_f32_e32 v3, v16, v3
	v_fmac_f32_e32 v14, v149, v133
	v_mul_f32_e32 v5, v5, v15
	v_fmac_f32_e32 v3, v155, v12
	v_mul_f32_e32 v148, v14, v5
	v_fmac_f32_e32 v148, v3, v13
	v_add_f32_e32 v3, v175, v207
	v_mul_f32_e32 v3, 0xbfb8aa3b, v3
	v_exp_f32_e32 v3, v3
	v_sqrt_f32_e32 v6, v6
	v_fma_f32 v7, v142, v11, v150
	v_fmac_f32_e32 v7, v144, v132
	v_add_f32_e32 v3, 1.0, v3
	v_rcp_f32_e32 v3, v3
	v_fmac_f32_e32 v7, v146, v133
	v_fmac_f32_e32 v7, v149, v134
	v_mul_f32_e32 v12, v154, v12
	v_mul_f32_e32 v3, v3, v6
	v_mul_f32_e32 v6, v7, v3
	v_add_f32_e32 v3, v175, v235
	v_mul_f32_e32 v3, 0xbfb8aa3b, v3
	v_exp_f32_e32 v3, v3
	v_mul_f32_e32 v5, v12, v13
	v_mul_f32_e32 v9, v5, v2
	v_sqrt_f32_e32 v8, v8
	v_add_f32_e32 v3, 1.0, v3
	v_rcp_f32_e32 v5, v3
	v_fma_f32 v7, v142, v132, v150
	v_fmac_f32_e32 v7, v144, v133
	v_fmac_f32_e32 v7, v146, v134
	v_mov_b32_e32 v3, v135
	v_pk_fma_f32 v[2:3], v[148:149], v[2:3], v[6:7]
	v_mul_f32_e32 v5, v5, v8
	v_pk_mul_f32 v[2:3], v[2:3], v[4:5]
	s_mov_b64 s[6:7], 0x3000
	v_mov_b32_e32 v114, v133
	v_mov_b32_e32 v113, v134
	v_add_f32_e32 v155, v2, v3
	v_mul_f32_e32 v154, v9, v4
	v_lshl_add_u64 v[0:1], v[0:1], 0, s[6:7]
	v_add_u32_e32 v10, 0x400, v10
	s_and_b64 vcc, exec, s[0:1]
	s_cbranch_vccnz .LBB0_539
	v_mov_b32_e32 v11, v135
	s_waitcnt vmcnt(0)
	v_lshlrev_b32_e32 v136, 16, v198
	v_lshlrev_b32_e32 v137, 16, v199
	v_lshlrev_b32_e32 v138, 16, v200
	v_lshlrev_b32_e32 v139, 16, v201
	v_mov_b64_e32 v[132:133], v[136:137]
	v_mov_b64_e32 v[134:135], v[138:139]
	s_branch .LBB0_541
